# attention FIXM loop: four loop-invariant LDS fragment address adds moved to the preheader (12 fewer VALU per iteration in total with the x+0 folds)
# speedup vs baseline: 1.0090x; 1.0015x over previous
.LBB0_896:
	s_andn2_saveexec_b64 s[44:45], s[44:45]
	s_cbranch_execz .LBB0_876
	v_mov_b32_e32 v129, v250
	s_waitcnt lgkmcnt(0)
	s_barrier
	v_readlane_b32 s9, v254, 52
	v_lshlrev_b32_e32 v2, 4, v129
	v_lshlrev_b32_e32 v3, 1, v129
	v_lshrrev_b32_e32 v131, 1, v129
	v_lshlrev_b32_e32 v0, 3, v129
	v_xor_b32_e32 v4, v2, v129
	v_and_b32_e32 v2, 19, v129
	v_and_b32_e32 v3, 8, v3
	v_and_b32_e32 v5, 4, v131
	v_ashrrev_i32_e32 v128, 3, v129
	v_and_b32_e32 v130, 56, v0
	v_or3_b32 v5, v3, v2, v5
	v_mov_b64_e32 v[2:3], s[40:41]
	v_mad_i64_i32 v[0:1], s[2:3], v128, s21, 0
	v_lshlrev_b32_e32 v176, 1, v130
	v_mad_i64_i32 v[2:3], s[2:3], v128, s33, v[2:3]
	v_lshl_add_u64 v[132:133], v[2:3], 0, v[176:177]
	v_lshlrev_b32_e32 v2, 7, v128
	s_movk_i32 s2, 0x70
	v_and_or_b32 v142, v4, s2, v2
	s_mov_b32 s2, 0xd8000
	v_lshl_add_u64 v[0:1], v[0:1], 1, s[42:43]
	v_add_co_u32_e32 v2, vcc, s2, v132
	v_lshl_add_u64 v[0:1], v[0:1], 0, v[176:177]
	v_lshrrev_b32_e32 v40, 1, v5
	v_bfe_u32 v138, v129, 5, 1
	s_waitcnt vmcnt(4)
	ds_write_b128 v142, v[64:67] offset:16384
	ds_write_b128 v142, v[68:71] offset:24576
	ds_write_b128 v142, v[72:75]
	ds_write_b128 v142, v[76:79] offset:8192
	v_addc_co_u32_e32 v3, vcc, 0, v133, vcc
	global_load_dwordx4 v[112:115], v[2:3], off offset:2048
	global_load_dwordx4 v[116:119], v[0:1], off offset:128
	v_bitop3_b32 v0, v40, v138, 7 bitop3:0x6c
	v_lshlrev_b32_e32 v143, 7, v5
	v_lshlrev_b32_e32 v145, 4, v0
	s_waitcnt lgkmcnt(0)
	s_barrier
	v_or_b32_e32 v41, v143, v145
	ds_read_b128 v[0:3], v41 offset:16384
	ds_read_b128 v[4:7], v41 offset:20480
	s_waitcnt lgkmcnt(0)
	v_mfma_f32_32x32x16_bf16 v[16:31], v[0:3], v[96:99], 0
	v_or_b32_e32 v32, 2, v138
	v_bitop3_b32 v32, v40, v32, 7 bitop3:0x6c
	v_lshlrev_b32_e32 v146, 4, v32
	v_or_b32_e32 v42, v143, v146
	ds_read_b128 v[32:35], v42 offset:16384
	ds_read_b128 v[36:39], v42 offset:20480
	v_lshrrev_b32_e32 v73, 5, v129
	v_bfe_u32 v74, v129, 1, 3
	v_mfma_f32_32x32x16_bf16 v[0:15], v[4:7], v[96:99], 0
	s_lshr_b32 s2, s21, 6
	v_mad_i64_i32 v[134:135], s[18:19], v128, s33, 0
	s_add_i32 s2, s2, -1
	v_and_b32_e32 v148, 31, v129
	v_lshlrev_b32_e32 v75, 7, v148
	s_mov_b32 s3, 5
	s_waitcnt lgkmcnt(1)
	v_mfma_f32_32x32x16_bf16 v[16:31], v[32:35], v[100:103], v[16:31]
	v_or_b32_e32 v32, 4, v138
	v_bitop3_b32 v32, v40, v32, 7 bitop3:0x6c
	v_lshlrev_b32_e32 v147, 4, v32
	v_or_b32_e32 v43, v143, v147
	s_waitcnt lgkmcnt(0)
	v_mfma_f32_32x32x16_bf16 v[0:15], v[36:39], v[100:103], v[0:15]
	ds_read_b128 v[32:35], v43 offset:16384
	ds_read_b128 v[36:39], v43 offset:20480
	s_waitcnt lgkmcnt(1)
	v_mfma_f32_32x32x16_bf16 v[16:31], v[32:35], v[104:107], v[16:31]
	v_or_b32_e32 v32, 6, v138
	v_bitop3_b32 v32, v40, v32, 7 bitop3:0x6c
	v_lshlrev_b32_e32 v149, 4, v32
	v_or_b32_e32 v72, v143, v149
	ds_read_b128 v[32:35], v72 offset:16384
	s_waitcnt lgkmcnt(1)
	v_mfma_f32_32x32x16_bf16 v[0:15], v[36:39], v[104:107], v[0:15]
	ds_read_b128 v[36:39], v72 offset:20480
	s_waitcnt lgkmcnt(1)
	v_mfma_f32_32x32x16_bf16 v[16:31], v[32:35], v[108:111], v[16:31]
	s_waitcnt lgkmcnt(0)
	v_mfma_f32_32x32x16_bf16 v[0:15], v[36:39], v[108:111], v[0:15]
	s_nop 9
	v_exp_f32_e32 v32, v16
	v_exp_f32_e32 v33, v17
	v_exp_f32_e32 v34, v18
	v_exp_f32_e32 v35, v19
	v_exp_f32_e32 v37, v20
	v_exp_f32_e32 v38, v21
	v_add_f32_e32 v16, 0, v32
	v_add_f32_e32 v17, 0, v33
	v_add_f32_e32 v36, 0, v34
	v_add_f32_e32 v39, 0, v35
	v_add_f32_e32 v40, v37, v16
	v_add_f32_e32 v44, v38, v17
	v_exp_f32_e32 v45, v22
	v_exp_f32_e32 v46, v23
	ds_read_b128 v[16:19], v41 offset:24576
	ds_read_b128 v[20:23], v41 offset:28672
	s_waitcnt lgkmcnt(1)
	v_mfma_f32_32x32x16_bf16 v[48:63], v[16:19], v[96:99], 0
	v_exp_f32_e32 v41, v24
	v_add_f32_e32 v36, v45, v36
	v_add_f32_e32 v39, v46, v39
	ds_read_b128 v[64:67], v42 offset:24576
	ds_read_b128 v[68:71], v42 offset:28672
	v_exp_f32_e32 v42, v25
	v_add_f32_e32 v24, v41, v40
	v_exp_f32_e32 v40, v26
	v_exp_f32_e32 v47, v27
	v_exp_f32_e32 v28, v28
	v_exp_f32_e32 v29, v29
	v_exp_f32_e32 v30, v30
	v_exp_f32_e32 v31, v31
	v_exp_f32_e32 v77, v0
	v_exp_f32_e32 v78, v1
	v_add_f32_e32 v25, v42, v44
	s_waitcnt lgkmcnt(1)
	v_mfma_f32_32x32x16_bf16 v[48:63], v[64:67], v[100:103], v[48:63]
	v_add_f32_e32 v26, v40, v36
	v_add_f32_e32 v27, v47, v39
	v_cvt_pk_bf16_f32 v80, v32, v33
	v_cvt_pk_bf16_f32 v81, v34, v35
	v_cvt_pk_bf16_f32 v82, v37, v38
	v_cvt_pk_bf16_f32 v83, v45, v46
	v_add_f32_e32 v24, v28, v24
	v_add_f32_e32 v25, v29, v25
	v_exp_f32_e32 v4, v4
	v_add_f32_e32 v76, v30, v26
	v_add_f32_e32 v0, v31, v27
	v_add_f32_e32 v79, v77, v24
	v_add_f32_e32 v88, v78, v25
	ds_read_b128 v[16:19], v43 offset:24576
	ds_read_b128 v[24:27], v43 offset:28672
	v_cvt_pk_bf16_f32 v86, v28, v29
	v_exp_f32_e32 v28, v2
	v_exp_f32_e32 v29, v3
	v_exp_f32_e32 v5, v5
	s_waitcnt lgkmcnt(1)
	v_mfma_f32_32x32x16_bf16 v[48:63], v[16:19], v[104:107], v[48:63]
	v_cvt_pk_bf16_f32 v84, v41, v42
	v_cvt_pk_bf16_f32 v85, v40, v47
	v_exp_f32_e32 v6, v6
	v_exp_f32_e32 v7, v7
	v_cvt_pk_bf16_f32 v87, v30, v31
	v_add_f32_e32 v30, v28, v76
	v_add_f32_e32 v31, v29, v0
	v_mfma_f32_32x32x16_bf16 v[32:47], v[20:23], v[96:99], 0
	ds_read_b128 v[0:3], v72 offset:24576
	ds_read_b128 v[20:23], v72 offset:28672
	v_add_f32_e32 v64, v4, v79
	v_add_f32_e32 v65, v5, v88
	v_add_f32_e32 v30, v6, v30
	v_exp_f32_e32 v8, v8
	v_exp_f32_e32 v9, v9
	v_add_f32_e32 v31, v7, v31
	v_cvt_pk_bf16_f32 v90, v4, v5
	v_exp_f32_e32 v4, v10
	v_exp_f32_e32 v5, v11
	v_exp_f32_e32 v11, v13
	v_cvt_pk_bf16_f32 v91, v6, v7
	v_exp_f32_e32 v7, v12
	s_waitcnt lgkmcnt(1)
	v_mfma_f32_32x32x16_bf16 v[48:63], v[0:3], v[108:111], v[48:63]
	v_exp_f32_e32 v0, v14
	v_exp_f32_e32 v1, v15
	v_add_f32_e32 v64, v8, v64
	v_add_f32_e32 v65, v9, v65
	v_cvt_pk_bf16_f32 v88, v77, v78
	v_cvt_pk_bf16_f32 v89, v28, v29
	v_add_f32_e32 v6, v4, v30
	v_mfma_f32_32x32x16_bf16 v[32:47], v[68:71], v[100:103], v[32:47]
	v_add_f32_e32 v10, v5, v31
	v_mov_b32_e32 v16, 0
	v_add_f32_e32 v12, v7, v64
	v_add_f32_e32 v2, v11, v65
	v_add_f32_e32 v3, v0, v6
	v_add_f32_e32 v6, v1, v10
	v_mfma_f32_32x32x16_bf16 v[32:47], v[24:27], v[104:107], v[32:47]
	v_cvt_pk_bf16_f32 v95, v0, v1
	v_add_f32_e32 v0, v12, v2
	v_add_f32_e32 v1, v3, v6
	v_add_f32_e32 v0, v0, v1
	v_add_f32_e32 v150, 0, v0
	v_bitop3_b32 v0, v73, v74, 1 bitop3:0x6c
	v_lshlrev_b32_e32 v2, 4, v0
	v_bitop3_b32 v0, v138, v74, 2 bitop3:0x36
	v_lshlrev_b32_e32 v3, 4, v0
	v_bitop3_b32 v0, v138, v74, 4 bitop3:0x36
	v_cvt_pk_bf16_f32 v93, v4, v5
	v_lshlrev_b32_e32 v4, 4, v0
	v_bitop3_b32 v0, v138, v74, 6 bitop3:0x36
	v_lshlrev_b32_e32 v5, 4, v0
	v_and_b32_e32 v0, 7, v129
	v_cvt_pk_bf16_f32 v92, v8, v9
	v_cvt_pk_bf16_f32 v94, v7, v11
	v_lshlrev_b32_e32 v176, 4, v0
	v_lshlrev_b32_e32 v0, 1, v128
	s_waitcnt lgkmcnt(0)
	s_barrier
	v_mad_i64_i32 v[0:1], s[18:19], v0, s21, v[176:177]
	s_add_u32 s18, s9, s38
	v_readlane_b32 s9, v254, 53
	s_addc_u32 s19, s9, s39
	s_waitcnt lgkmcnt(0)
	v_mfma_f32_32x32x16_bf16 v[32:47], v[20:23], v[108:111], v[32:47]
	v_lshl_add_u64 v[136:137], s[18:19], 0, v[0:1]
	v_add_u32_e32 v144, v75, v2
	v_add_u32_e32 v141, v75, v3
	v_add_u32_e32 v140, v75, v4
	v_add_u32_e32 v139, v75, v5
	v_mov_b32_e32 v17, v16
	v_mov_b32_e32 v18, v16
	v_mov_b32_e32 v19, v16
	v_mov_b32_e32 v20, v16
	v_mov_b32_e32 v21, v16
	v_mov_b32_e32 v22, v16
	v_mov_b32_e32 v23, v16
	v_mov_b32_e32 v24, v16
	v_mov_b32_e32 v25, v16
	v_mov_b32_e32 v26, v16
	v_mov_b32_e32 v27, v16
	v_mov_b32_e32 v28, v16
	v_mov_b32_e32 v29, v16
	v_mov_b32_e32 v30, v16
	v_mov_b32_e32 v31, v16
	v_mov_b32_e32 v0, v16
	v_mov_b32_e32 v1, v16
	v_mov_b32_e32 v2, v16
	v_mov_b32_e32 v3, v16
	v_mov_b32_e32 v4, v16
	v_mov_b32_e32 v5, v16
	v_mov_b32_e32 v6, v16
	v_mov_b32_e32 v7, v16
	v_mov_b32_e32 v8, v16
	v_mov_b32_e32 v9, v16
	v_mov_b32_e32 v10, v16
	v_mov_b32_e32 v11, v16
	v_mov_b32_e32 v12, v16
	v_mov_b32_e32 v13, v16
	v_mov_b32_e32 v14, v16
	v_mov_b32_e32 v15, v16
	v_add_u32_e32 v164, v143, v145
	v_add_u32_e32 v165, v143, v146
	v_add_u32_e32 v166, v143, v147
	v_add_u32_e32 v167, v143, v149
.LBB0_898:
	s_add_i32 s9, s3, -1
	s_min_u32 s9, s9, s2
	s_lshl_b32 s9, s9, 6
	s_waitcnt vmcnt(1)
	ds_write_b128 v142, v[112:115] offset:16384
	s_waitcnt vmcnt(0)
	ds_write_b128 v142, v[116:119] offset:24576
	v_mad_u64_u32 v[64:65], s[18:19], s9, v237, v[132:133]
	global_load_dwordx4 v[120:123], v[64:65], off offset:2048
	global_load_dwordx4 v[124:127], v[136:137], off offset:-128
	ds_read_b128 v[64:67], v144 offset:8192
	ds_read_b128 v[68:71], v144 offset:12288
	ds_read_b128 v[72:75], v141 offset:8192
	ds_read_b128 v[76:79], v141 offset:12288
	v_exp_f32_e32 v151, v48
	v_exp_f32_e32 v152, v49
	s_waitcnt lgkmcnt(3)
	v_mfma_f32_32x32x16_bf16 v[16:31], v[64:67], v[80:83], v[16:31]
	v_exp_f32_e32 v153, v50
	v_exp_f32_e32 v154, v51
	ds_read_b128 v[48:51], v140 offset:8192
	ds_read_b128 v[64:67], v140 offset:12288
	v_exp_f32_e32 v155, v52
	s_waitcnt lgkmcnt(4)
	v_mfma_f32_32x32x16_bf16 v[0:15], v[68:71], v[80:83], v[0:15]
	v_exp_f32_e32 v156, v53
	v_exp_f32_e32 v159, v54
	v_exp_f32_e32 v160, v55
	v_exp_f32_e32 v162, v57
	s_waitcnt lgkmcnt(3)
	v_mfma_f32_32x32x16_bf16 v[16:31], v[72:75], v[84:87], v[16:31]
	ds_read_b128 v[68:71], v139 offset:8192
	ds_read_b128 v[80:83], v139 offset:12288
	v_add_f32_e32 v157, v155, v151
	v_add_f32_e32 v158, v156, v152
	ds_read_b128 v[52:55], v164
	ds_read_b128 v[72:75], v164 offset:4096
	v_add_f32_e32 v161, v159, v153
	s_waitcnt lgkmcnt(6)
	v_mfma_f32_32x32x16_bf16 v[0:15], v[76:79], v[84:87], v[0:15]
	v_exp_f32_e32 v77, v56
	v_add_f32_e32 v76, v160, v154
	v_exp_f32_e32 v62, v62
	ds_read_b128 v[112:115], v165
	ds_read_b128 v[116:119], v165 offset:4096
	v_cvt_pk_bf16_f32 v56, v151, v152
	s_waitcnt lgkmcnt(7)
	v_mfma_f32_32x32x16_bf16 v[16:31], v[48:51], v[88:91], v[16:31]
	v_exp_f32_e32 v49, v58
	v_exp_f32_e32 v50, v59
	v_add_f32_e32 v48, v77, v157
	v_add_f32_e32 v51, v162, v158
	v_add_f32_e32 v78, v49, v161
	v_add_f32_e32 v76, v50, v76
	s_waitcnt lgkmcnt(6)
	v_mfma_f32_32x32x16_bf16 v[0:15], v[64:67], v[88:91], v[0:15]
	v_exp_f32_e32 v60, v60
	v_add_f32_e32 v151, v62, v78
	v_exp_f32_e32 v61, v61
	v_exp_f32_e32 v63, v63
	v_cvt_pk_bf16_f32 v59, v159, v160
	v_exp_f32_e32 v160, v33
	s_waitcnt lgkmcnt(5)
	v_mfma_f32_32x32x16_bf16 v[16:31], v[68:71], v[92:95], v[16:31]
	v_cvt_pk_bf16_f32 v57, v153, v154
	v_cvt_pk_bf16_f32 v58, v155, v156
	v_add_f32_e32 v48, v60, v48
	v_add_f32_e32 v51, v61, v51
	v_cvt_pk_bf16_f32 v49, v49, v50
	s_waitcnt lgkmcnt(4)
	v_mfma_f32_32x32x16_bf16 v[0:15], v[80:83], v[92:95], v[0:15]
	v_exp_f32_e32 v95, v32
	v_add_f32_e32 v32, v63, v76
	v_add_f32_e32 v163, v160, v51
	v_add_f32_e32 v161, v95, v48
	v_cvt_pk_bf16_f32 v48, v77, v162
	v_cvt_pk_bf16_f32 v51, v62, v63
	s_waitcnt lgkmcnt(3)
	v_mfma_f32_32x32x16_bf16 v[78:93], v[52:55], v[96:99], 0
	v_cvt_pk_bf16_f32 v50, v60, v61
	v_exp_f32_e32 v60, v34
	v_exp_f32_e32 v61, v35
	v_exp_f32_e32 v36, v36
	v_exp_f32_e32 v37, v37
	v_exp_f32_e32 v38, v38
	v_exp_f32_e32 v39, v39
	s_waitcnt lgkmcnt(2)
	v_mfma_f32_32x32x16_bf16 v[62:77], v[72:75], v[96:99], 0
	ds_read_b128 v[52:55], v166
	ds_read_b128 v[152:155], v166 offset:4096
	v_add_f32_e32 v151, v60, v151
	v_add_f32_e32 v162, v61, v32
	s_waitcnt lgkmcnt(3)
	v_mfma_f32_32x32x16_bf16 v[78:93], v[112:115], v[100:103], v[78:93]
	v_add_f32_e32 v112, v36, v161
	v_add_f32_e32 v113, v37, v163
	v_add_f32_e32 v114, v38, v151
	v_exp_f32_e32 v115, v40
	v_add_f32_e32 v40, v39, v162
	ds_read_b128 v[32:35], v167
	ds_read_b128 v[156:159], v167 offset:4096
	s_waitcnt lgkmcnt(4)
	v_mfma_f32_32x32x16_bf16 v[62:77], v[116:119], v[100:103], v[62:77]
	v_exp_f32_e32 v116, v41
	v_add_f32_e32 v41, v115, v112
	s_min_u32 s9, s3, s2
	s_lshl_b32 s9, s9, 6
	v_add_f32_e32 v112, v116, v113
	s_waitcnt lgkmcnt(3)
	v_mfma_f32_32x32x16_bf16 v[78:93], v[52:55], v[104:107], v[78:93]
	v_cvt_pk_bf16_f32 v54, v36, v37
	v_exp_f32_e32 v37, v42
	v_cvt_pk_bf16_f32 v55, v38, v39
	v_exp_f32_e32 v38, v43
	v_exp_f32_e32 v39, v44
	v_exp_f32_e32 v44, v45
	v_exp_f32_e32 v45, v46
	v_exp_f32_e32 v46, v47
	v_cvt_pk_bf16_f32 v52, v95, v160
	v_cvt_pk_bf16_f32 v53, v60, v61
	v_add_f32_e32 v36, v37, v114
	v_add_f32_e32 v43, v38, v40
	v_add_f32_e32 v40, v39, v41
	v_add_f32_e32 v42, v44, v112
	v_add_f32_e32 v41, v45, v36
	v_add_f32_e32 v43, v46, v43
	v_cvt_pk_bf16_f32 v36, v115, v116
	v_cvt_pk_bf16_f32 v37, v37, v38
	v_cvt_pk_bf16_f32 v38, v39, v44
	v_cvt_pk_bf16_f32 v39, v45, v46
	s_waitcnt lgkmcnt(1)
	v_mfma_f32_32x32x16_bf16 v[78:93], v[32:35], v[108:111], v[78:93]
	s_waitcnt lgkmcnt(0)
	s_barrier
	v_mad_u64_u32 v[32:33], s[18:19], s9, v237, v[132:133]
	global_load_dwordx4 v[112:115], v[32:33], off offset:2048
	global_load_dwordx4 v[116:119], v[136:137], off
	v_add_f32_e64 v32, v40, v42
	v_add_f32_e64 v33, v41, v43
	s_waitcnt vmcnt(3)
	ds_write_b128 v142, v[120:123]
	s_waitcnt vmcnt(2)
	ds_write_b128 v142, v[124:127] offset:8192
	v_mfma_f32_32x32x16_bf16 v[62:77], v[152:155], v[104:107], v[62:77]
	v_add_f32_e32 v32, v32, v33
	v_add_f32_e32 v150, v150, v32
	s_waitcnt lgkmcnt(2)
	v_mfma_f32_32x32x16_bf16 v[62:77], v[156:159], v[108:111], v[62:77]
	ds_read_b128 v[32:35], v144 offset:24576
	ds_read_b128 v[40:43], v144 offset:28672
	ds_read_b128 v[44:47], v141 offset:24576
	ds_read_b128 v[120:123], v141 offset:28672
	v_exp_f32_e32 v60, v78
	s_waitcnt lgkmcnt(3)
	v_mfma_f32_32x32x16_bf16 v[16:31], v[32:35], v[56:59], v[16:31]
	v_exp_f32_e32 v61, v79
	v_exp_f32_e32 v95, v80
	v_exp_f32_e32 v81, v81
	ds_read_b128 v[152:155], v140 offset:24576
	ds_read_b128 v[156:159], v140 offset:28672
	s_waitcnt lgkmcnt(4)
	v_mfma_f32_32x32x16_bf16 v[0:15], v[40:43], v[56:59], v[0:15]
	v_exp_f32_e32 v82, v82
	v_exp_f32_e32 v83, v83
	v_add_f32_e32 v78, v82, v60
	v_add_f32_e32 v79, v83, v61
	s_waitcnt lgkmcnt(2)
	v_mfma_f32_32x32x16_bf16 v[0:15], v[120:123], v[48:51], v[0:15]
	ds_read_b128 v[56:59], v139 offset:24576
	ds_read_b128 v[160:163], v139 offset:28672
	ds_read_b128 v[40:43], v164 offset:16384
	ds_read_b128 v[32:35], v164 offset:20480
	v_cvt_pk_bf16_f32 v82, v82, v83
	v_exp_f32_e32 v151, v62
	v_exp_f32_e32 v64, v64
	v_exp_f32_e32 v65, v65
	v_mfma_f32_32x32x16_bf16 v[16:31], v[44:47], v[48:51], v[16:31]
	v_exp_f32_e32 v44, v84
	v_exp_f32_e32 v45, v85
	v_exp_f32_e32 v84, v86
	v_exp_f32_e32 v85, v87
	v_add_f32_e32 v46, v44, v95
	v_add_f32_e32 v47, v45, v81
	v_add_f32_e32 v48, v84, v78
	s_waitcnt lgkmcnt(4)
	v_mfma_f32_32x32x16_bf16 v[0:15], v[156:159], v[52:55], v[0:15]
	v_add_f32_e32 v49, v85, v79
	v_exp_f32_e32 v78, v88
	v_exp_f32_e32 v79, v89
	v_exp_f32_e32 v87, v92
	v_cvt_pk_bf16_f32 v83, v44, v45
	v_exp_f32_e32 v44, v90
	v_mfma_f32_32x32x16_bf16 v[16:31], v[152:155], v[52:55], v[16:31]
	v_exp_f32_e32 v45, v91
	v_exp_f32_e32 v92, v93
	v_add_f32_e32 v46, v78, v46
	v_add_f32_e32 v47, v79, v47
	ds_read_b128 v[124:127], v165 offset:16384
	ds_read_b128 v[120:123], v165 offset:20480
	s_waitcnt lgkmcnt(4)
	v_mfma_f32_32x32x16_bf16 v[0:15], v[160:163], v[36:39], v[0:15]
	v_exp_f32_e32 v160, v63
	v_cvt_pk_bf16_f32 v80, v60, v61
	v_cvt_pk_bf16_f32 v81, v95, v81
	v_add_f32_e32 v48, v44, v48
	v_add_f32_e32 v49, v45, v49
	v_add_f32_e32 v46, v87, v46
	v_add_f32_e32 v47, v92, v47
	v_mfma_f32_32x32x16_bf16 v[16:31], v[56:59], v[36:39], v[16:31]
	v_add_f32_e32 v161, v151, v48
	v_add_f32_e32 v162, v160, v49
	v_cvt_pk_bf16_f32 v84, v84, v85
	v_cvt_pk_bf16_f32 v85, v78, v79
	v_cvt_pk_bf16_f32 v86, v44, v45
	v_add_f32_e32 v78, v64, v46
	v_add_f32_e32 v79, v65, v47
	s_waitcnt lgkmcnt(3)
	v_mfma_f32_32x32x16_bf16 v[48:63], v[40:43], v[96:99], 0
	ds_read_b128 v[88:91], v166 offset:16384
	ds_read_b128 v[152:155], v166 offset:20480
	v_exp_f32_e32 v66, v66
	v_exp_f32_e32 v67, v67
	v_exp_f32_e32 v68, v68
	v_exp_f32_e32 v69, v69
	v_cvt_pk_bf16_f32 v87, v87, v92
	s_waitcnt lgkmcnt(4)
	v_mfma_f32_32x32x16_bf16 v[32:47], v[32:35], v[96:99], 0
	ds_read_b128 v[156:159], v167 offset:16384
	ds_read_b128 v[92:95], v167 offset:20480
	v_add_f32_e32 v161, v66, v161
	v_add_f32_e32 v162, v67, v162
	v_add_f32_e32 v78, v68, v78
	v_add_f32_e32 v79, v69, v79
	s_waitcnt lgkmcnt(5)
	v_mfma_f32_32x32x16_bf16 v[48:63], v[124:127], v[100:103], v[48:63]
	v_exp_f32_e32 v70, v70
	v_exp_f32_e32 v71, v71
	s_add_i32 s9, s3, 2
	s_add_i32 s3, s3, -2
	v_lshl_add_u64 v[136:137], v[136:137], 0, s[22:23]
	s_waitcnt lgkmcnt(4)
	v_mfma_f32_32x32x16_bf16 v[32:47], v[120:123], v[100:103], v[32:47]
	v_add_f32_e32 v120, v70, v161
	v_add_f32_e32 v121, v71, v162
	s_cmp_lt_u32 s3, s2
	s_mov_b32 s3, s9
	s_waitcnt lgkmcnt(3)
	v_mfma_f32_32x32x16_bf16 v[48:63], v[88:91], v[104:107], v[48:63]
	v_cvt_pk_bf16_f32 v91, v68, v69
	v_exp_f32_e32 v68, v72
	v_exp_f32_e32 v69, v73
	v_exp_f32_e32 v72, v74
	v_exp_f32_e32 v73, v75
	v_exp_f32_e32 v74, v76
	v_exp_f32_e32 v75, v77
	s_waitcnt lgkmcnt(2)
	v_mfma_f32_32x32x16_bf16 v[32:47], v[152:155], v[104:107], v[32:47]
	v_cvt_pk_bf16_f32 v88, v151, v160
	v_cvt_pk_bf16_f32 v89, v64, v65
	v_cvt_pk_bf16_f32 v90, v66, v67
	v_add_f32_e32 v65, v68, v78
	v_add_f32_e32 v67, v69, v79
	s_waitcnt lgkmcnt(1)
	v_mfma_f32_32x32x16_bf16 v[48:63], v[156:159], v[108:111], v[48:63]
	v_add_f32_e32 v64, v72, v120
	v_add_f32_e32 v66, v73, v121
	v_add_f32_e32 v65, v74, v65
	v_add_f32_e32 v67, v75, v67
	s_waitcnt lgkmcnt(0)
	v_mfma_f32_32x32x16_bf16 v[32:47], v[92:95], v[108:111], v[32:47]
	v_cvt_pk_bf16_f32 v92, v70, v71
	v_cvt_pk_bf16_f32 v93, v68, v69
	v_cvt_pk_bf16_f32 v94, v72, v73
	v_cvt_pk_bf16_f32 v95, v74, v75
	v_add_f32_e64 v64, v64, v66
	v_add_f32_e64 v65, v65, v67
	s_waitcnt lgkmcnt(0)
	s_barrier
	v_add_f32_e32 v64, v64, v65
	v_add_f32_e32 v150, v150, v64
	s_cbranch_scc1 .LBB0_898
	v_ashrrev_i32_e32 v64, 1, v129
	v_and_or_b32 v132, v64, s88, v148
	v_mov_b64_e32 v[64:65], s[12:13]
	v_mad_i64_i32 v[64:65], s[2:3], v132, s33, v[64:65]
	v_lshlrev_b32_e32 v176, 4, v138
	s_waitcnt vmcnt(1)
	ds_write_b128 v142, v[112:115] offset:16384
	s_waitcnt vmcnt(0)
	ds_write_b128 v142, v[116:119] offset:24576
	v_lshl_add_u64 v[64:65], v[64:65], 0, v[176:177]
	global_load_dwordx4 v[124:127], v[64:65], off offset:2560
	global_load_dwordx4 v[120:123], v[64:65], off offset:2592
	global_load_dwordx4 v[116:119], v[64:65], off offset:2624
	global_load_dwordx4 v[112:115], v[64:65], off offset:2656
	v_mov_b64_e32 v[64:65], s[14:15]
	v_mad_i64_i32 v[64:65], s[2:3], v132, s33, v[64:65]
	v_and_b32_e32 v66, 16, v131
	v_mov_b32_e32 v67, v177
	v_lshl_add_u64 v[64:65], v[64:65], 0, v[66:67]
	global_load_dwordx4 v[96:99], v[64:65], off offset:1024
	global_load_dwordx4 v[100:103], v[64:65], off offset:1056
	global_load_dwordx4 v[104:107], v[64:65], off offset:1088
	global_load_dwordx4 v[108:111], v[64:65], off offset:1120
	v_lshl_add_u64 v[64:65], s[34:35], 0, v[134:135]
	v_lshlrev_b32_e32 v76, 1, v130
	v_mov_b32_e32 v77, v177
	v_lshl_add_u64 v[72:73], v[64:65], 0, v[76:77]
	s_mov_b32 s2, 0x48000
	v_add_co_u32_e32 v68, vcc, s2, v72
	s_mov_b32 s2, 0x90000
	s_nop 0
	v_addc_co_u32_e32 v69, vcc, 0, v73, vcc
	global_load_dwordx4 v[64:67], v[72:73], off offset:2048
	v_ashrrev_i32_e32 v133, 31, v132
	global_load_dwordx4 v[68:71], v[68:69], off offset:2048
	v_add_co_u32_e32 v72, vcc, s2, v72
	v_mad_i64_i32 v[78:79], s[2:3], s8, v128, 0
	v_lshl_add_u64 v[78:79], v[78:79], 1, s[10:11]
	v_addc_co_u32_e32 v73, vcc, 0, v73, vcc
	v_lshl_add_u64 v[76:77], v[78:79], 0, v[76:77]
	global_load_dwordx4 v[72:75], v[72:73], off offset:2048
	s_nop 0
	global_load_dwordx4 v[76:79], v[76:77], off
	ds_read_b128 v[128:131], v144 offset:8192
	ds_read_b128 v[134:137], v144 offset:12288
	ds_read_b128 v[146:149], v141 offset:8192
	ds_read_b128 v[152:155], v141 offset:12288
	v_exp_f32_e32 v138, v48
	v_exp_f32_e32 v142, v49
	s_waitcnt lgkmcnt(3)
	v_mfma_f32_32x32x16_bf16 v[16:31], v[128:131], v[80:83], v[16:31]
	v_exp_f32_e32 v151, v50
	v_add_f32_e32 v143, 0, v138
	v_add_f32_e32 v145, 0, v142
	v_exp_f32_e32 v156, v51
	ds_read_b128 v[48:51], v140 offset:8192
	ds_read_b128 v[128:131], v140 offset:12288
	v_exp_f32_e32 v52, v52
	s_waitcnt lgkmcnt(4)
	v_mfma_f32_32x32x16_bf16 v[0:15], v[134:137], v[80:83], v[0:15]
	v_exp_f32_e32 v53, v53
	v_exp_f32_e32 v54, v54
	v_exp_f32_e32 v55, v55
	v_add_f32_e32 v157, 0, v151
	v_add_f32_e32 v158, 0, v156
	v_add_f32_e32 v143, v52, v143
	s_waitcnt lgkmcnt(3)
	v_mfma_f32_32x32x16_bf16 v[16:31], v[146:149], v[84:87], v[16:31]
	v_add_f32_e32 v145, v53, v145
	v_add_f32_e32 v146, v54, v157
	ds_read_b128 v[80:83], v139 offset:8192
	ds_read_b128 v[134:137], v139 offset:12288
	v_exp_f32_e32 v56, v56
	v_exp_f32_e32 v57, v57
	v_exp_f32_e32 v58, v58
	s_waitcnt lgkmcnt(4)
	v_mfma_f32_32x32x16_bf16 v[0:15], v[152:155], v[84:87], v[0:15]
	v_add_f32_e32 v84, v55, v158
	v_exp_f32_e32 v59, v59
	v_exp_f32_e32 v60, v60
	v_exp_f32_e32 v32, v32
	v_exp_f32_e32 v33, v33
	v_exp_f32_e32 v34, v34
	s_waitcnt lgkmcnt(3)
	v_mfma_f32_32x32x16_bf16 v[16:31], v[48:51], v[88:91], v[16:31]
	v_cvt_pk_bf16_f32 v51, v54, v55
	v_exp_f32_e32 v54, v61
	v_exp_f32_e32 v55, v62
	v_exp_f32_e32 v61, v63
	v_exp_f32_e32 v35, v35
	v_add_f32_e32 v85, v56, v143
	v_add_f32_e32 v86, v57, v145
	v_add_f32_e32 v87, v58, v146
	v_add_f32_e32 v84, v59, v84
	v_cvt_pk_bf16_f32 v48, v138, v142
	v_cvt_pk_bf16_f32 v49, v151, v156
	v_cvt_pk_bf16_f32 v50, v52, v53
	v_add_f32_e32 v52, v60, v85
	v_add_f32_e32 v53, v54, v86
	v_add_f32_e32 v62, v55, v87
	v_add_f32_e32 v63, v61, v84
	v_exp_f32_e32 v36, v36
	v_exp_f32_e32 v37, v37
	v_exp_f32_e32 v38, v38
	v_exp_f32_e32 v39, v39
	s_waitcnt lgkmcnt(1)
	v_mfma_f32_32x32x16_bf16 v[16:31], v[80:83], v[92:95], v[16:31]
	v_add_f32_e32 v80, v32, v52
	v_add_f32_e32 v81, v33, v53
	v_cvt_pk_bf16_f32 v52, v56, v57
	v_cvt_pk_bf16_f32 v53, v58, v59
	v_cvt_pk_bf16_f32 v54, v60, v54
	v_cvt_pk_bf16_f32 v55, v55, v61
	v_add_f32_e32 v56, v34, v62
	v_add_f32_e32 v57, v35, v63
	v_exp_f32_e32 v40, v40
	v_add_f32_e32 v58, v36, v80
	v_add_f32_e32 v59, v37, v81
	v_add_f32_e32 v56, v38, v56
	v_exp_f32_e32 v41, v41
	v_add_f32_e32 v57, v39, v57
	v_mfma_f32_32x32x16_bf16 v[0:15], v[128:131], v[88:91], v[0:15]
	v_cvt_pk_bf16_f32 v32, v32, v33
	v_cvt_pk_bf16_f32 v33, v34, v35
	v_cvt_pk_bf16_f32 v34, v36, v37
	v_exp_f32_e32 v37, v42
	v_cvt_pk_bf16_f32 v35, v38, v39
	v_exp_f32_e32 v38, v43
	v_exp_f32_e32 v39, v44
	v_exp_f32_e32 v43, v45
	v_exp_f32_e32 v44, v46
	v_exp_f32_e32 v45, v47
	v_add_f32_e32 v58, v40, v58
	v_add_f32_e32 v59, v41, v59
	v_add_f32_e32 v36, v37, v56
	v_add_f32_e32 v42, v38, v57
	v_add_f32_e32 v56, v39, v58
	v_add_f32_e32 v58, v43, v59
	s_waitcnt lgkmcnt(0)
	v_mfma_f32_32x32x16_bf16 v[0:15], v[134:137], v[92:95], v[0:15]
	v_add_f32_e32 v57, v44, v36
	v_add_f32_e32 v59, v45, v42
	v_cvt_pk_bf16_f32 v36, v40, v41
	v_cvt_pk_bf16_f32 v37, v37, v38
	v_cvt_pk_bf16_f32 v38, v39, v43
	v_cvt_pk_bf16_f32 v39, v44, v45
	s_waitcnt lgkmcnt(0)
	s_barrier
	ds_read_b128 v[40:43], v144 offset:24576
	ds_read_b128 v[44:47], v144 offset:28672
	s_waitcnt lgkmcnt(1)
	v_mfma_f32_32x32x16_bf16 v[16:31], v[40:43], v[48:51], v[16:31]
	s_waitcnt lgkmcnt(0)
	v_mfma_f32_32x32x16_bf16 v[0:15], v[44:47], v[48:51], v[0:15]
	ds_read_b128 v[40:43], v141 offset:24576
	ds_read_b128 v[44:47], v141 offset:28672
	s_waitcnt lgkmcnt(1)
	v_mfma_f32_32x32x16_bf16 v[16:31], v[40:43], v[52:55], v[16:31]
	s_waitcnt lgkmcnt(0)
	v_mfma_f32_32x32x16_bf16 v[0:15], v[44:47], v[52:55], v[0:15]
	ds_read_b128 v[40:43], v140 offset:24576
	ds_read_b128 v[44:47], v140 offset:28672
	s_waitcnt lgkmcnt(1)
	v_mfma_f32_32x32x16_bf16 v[16:31], v[40:43], v[32:35], v[16:31]
	s_waitcnt lgkmcnt(0)
	v_mfma_f32_32x32x16_bf16 v[0:15], v[44:47], v[32:35], v[0:15]
	ds_read_b128 v[32:35], v139 offset:24576
	ds_read_b128 v[40:43], v139 offset:28672
	s_waitcnt lgkmcnt(1)
	v_mfma_f32_32x32x16_bf16 v[16:31], v[32:35], v[36:39], v[16:31]
	v_add_f32_e64 v32, v56, v58
	v_add_f32_e64 v33, v57, v59
	v_add_f32_e32 v32, v32, v33
	v_add_f32_e32 v32, v150, v32
	v_mov_b32_e32 v33, v32
	s_nop 1
	v_permlane32_swap_b32_e32 v32, v33
	v_add_f32_e32 v32, v32, v33
	v_div_scale_f32 v33, s[2:3], v32, v32, 1.0
	v_rcp_f32_e32 v34, v33
	s_waitcnt lgkmcnt(0)
	v_mfma_f32_32x32x16_bf16 v[0:15], v[40:43], v[36:39], v[0:15]
	s_waitcnt vmcnt(11)
	v_mov_b32_e32 v40, v127
	s_nop 1
	v_permlane32_swap_b32_e32 v125, v40
	v_fma_f32 v35, -v33, v34, 1.0
	v_fmac_f32_e32 v34, v35, v34
	v_div_scale_f32 v35, vcc, 1.0, v32, 1.0
	v_mul_f32_e32 v36, v35, v34
	v_fma_f32 v37, -v33, v36, v35
	v_fmac_f32_e32 v36, v37, v34
	v_fma_f32 v33, -v33, v36, v35
	v_div_fmas_f32 v33, v33, v34, v36
	v_mov_b32_e32 v35, v126
	v_div_fixup_f32 v34, v33, v32, 1.0
	s_nop 0
	v_permlane32_swap_b32_e32 v124, v35
	v_lshlrev_b32_e32 v38, 16, v124
	v_and_b32_e32 v39, 0xffff0000, v124
	v_mul_f32_e32 v16, v16, v34
	v_mul_f32_e32 v17, v17, v34
	v_mul_f32_e32 v18, v18, v34
	v_mul_f32_e32 v19, v19, v34
	v_mul_f32_e32 v16, v16, v38
	v_mul_f32_e32 v17, v17, v39
	v_lshlrev_b32_e32 v38, 16, v125
	v_and_b32_e32 v39, 0xffff0000, v125
	v_mul_f32_e32 v18, v18, v38
	v_mul_f32_e32 v19, v19, v39
	v_cvt_pk_bf16_f32 v16, v16, v17
	v_cvt_pk_bf16_f32 v17, v18, v19
	v_lshlrev_b32_e32 v18, 16, v35
	v_and_b32_e32 v19, 0xffff0000, v35
	v_mul_f32_e32 v20, v20, v34
	v_mul_f32_e32 v21, v21, v34
	v_mul_f32_e32 v22, v22, v34
	v_mul_f32_e32 v23, v23, v34
	v_mul_f32_e32 v18, v20, v18
	v_mul_f32_e32 v19, v21, v19
	v_lshlrev_b32_e32 v20, 16, v40
	v_and_b32_e32 v21, 0xffff0000, v40
	v_lshlrev_b64 v[32:33], 11, v[132:133]
	v_mul_f32_e32 v20, v22, v20
	v_mul_f32_e32 v21, v23, v21
	v_lshl_add_u64 v[32:33], s[6:7], 0, v[32:33]
	v_cvt_pk_bf16_f32 v18, v18, v19
	v_cvt_pk_bf16_f32 v19, v20, v21
	s_waitcnt vmcnt(10)
	v_mov_b32_e32 v22, v122
	v_lshl_add_u64 v[36:37], v[32:33], 0, v[176:177]
	v_permlane32_swap_b32_e32 v16, v18
	v_permlane32_swap_b32_e32 v17, v19
	v_permlane32_swap_b32_e32 v120, v22
	v_mov_b32_e32 v23, v123
	global_store_dwordx4 v[36:37], v[16:19], off offset:512
	s_nop 0
	v_permlane32_swap_b32_e32 v121, v23
	v_lshlrev_b32_e32 v16, 16, v120
	v_and_b32_e32 v17, 0xffff0000, v120
	v_mul_f32_e32 v18, v24, v34
	v_mul_f32_e32 v19, v25, v34
	v_mul_f32_e32 v20, v26, v34
	v_mul_f32_e32 v21, v27, v34
	v_mul_f32_e32 v16, v18, v16
	v_mul_f32_e32 v17, v19, v17
	v_lshlrev_b32_e32 v18, 16, v121
	v_and_b32_e32 v19, 0xffff0000, v121
	v_mul_f32_e32 v18, v20, v18
	v_mul_f32_e32 v19, v21, v19
	v_cvt_pk_bf16_f32 v16, v16, v17
	v_cvt_pk_bf16_f32 v17, v18, v19
	v_lshlrev_b32_e32 v18, 16, v22
	v_and_b32_e32 v19, 0xffff0000, v22
	v_mul_f32_e32 v20, v28, v34
	v_mul_f32_e32 v21, v29, v34
	v_mul_f32_e32 v0, v0, v34
	v_mul_f32_e32 v1, v1, v34
	v_mul_f32_e32 v18, v20, v18
	v_mul_f32_e32 v19, v21, v19
	v_lshlrev_b32_e32 v20, 16, v23
	v_and_b32_e32 v21, 0xffff0000, v23
	v_mul_f32_e32 v22, v30, v34
	v_mul_f32_e32 v23, v31, v34
	v_cvt_pk_bf16_f32 v18, v18, v19
	v_mul_f32_e32 v20, v22, v20
	v_mul_f32_e32 v21, v23, v21
	s_nop 0
	v_permlane32_swap_b32_e32 v16, v18
	v_cvt_pk_bf16_f32 v19, v20, v21
	s_nop 1
	v_permlane32_swap_b32_e32 v17, v19
	global_store_dwordx4 v[36:37], v[16:19], off offset:544
	v_mul_f32_e32 v2, v2, v34
	v_mul_f32_e32 v3, v3, v34
	v_mul_f32_e32 v4, v4, v34
	v_mul_f32_e32 v5, v5, v34
	s_waitcnt vmcnt(11)
	v_mov_b32_e32 v18, v118
	s_nop 1
	v_permlane32_swap_b32_e32 v116, v18
	v_mov_b32_e32 v19, v119
	s_nop 1
	v_permlane32_swap_b32_e32 v117, v19
	v_lshlrev_b32_e32 v16, 16, v116
	v_and_b32_e32 v17, 0xffff0000, v116
	v_mul_f32_e32 v0, v0, v16
	v_mul_f32_e32 v1, v1, v17
	v_lshlrev_b32_e32 v16, 16, v117
	v_and_b32_e32 v17, 0xffff0000, v117
	v_mul_f32_e32 v2, v2, v16
	v_mul_f32_e32 v3, v3, v17
	v_cvt_pk_bf16_f32 v0, v0, v1
	v_cvt_pk_bf16_f32 v1, v2, v3
	v_lshlrev_b32_e32 v2, 16, v18
	v_and_b32_e32 v3, 0xffff0000, v18
	v_mul_f32_e32 v2, v4, v2
	v_mul_f32_e32 v3, v5, v3
	v_lshlrev_b32_e32 v4, 16, v19
	v_and_b32_e32 v5, 0xffff0000, v19
	v_mul_f32_e32 v6, v6, v34
	v_mul_f32_e32 v7, v7, v34
	v_cvt_pk_bf16_f32 v2, v2, v3
	v_mul_f32_e32 v4, v6, v4
	v_mul_f32_e32 v5, v7, v5
	s_waitcnt vmcnt(10)
	v_mov_b32_e32 v6, v114
	v_cvt_pk_bf16_f32 v3, v4, v5
	v_permlane32_swap_b32_e32 v0, v2
	s_nop 0
	v_permlane32_swap_b32_e32 v1, v3
	v_permlane32_swap_b32_e32 v112, v6
	v_mov_b32_e32 v7, v115
	global_store_dwordx4 v[36:37], v[0:3], off offset:576
	s_nop 0
	v_permlane32_swap_b32_e32 v113, v7
	v_lshlrev_b32_e32 v0, 16, v112
	v_and_b32_e32 v1, 0xffff0000, v112
	v_mul_f32_e32 v2, v8, v34
	v_mul_f32_e32 v3, v9, v34
	v_mul_f32_e32 v4, v10, v34
	v_mul_f32_e32 v5, v11, v34
	v_mul_f32_e32 v0, v2, v0
	v_mul_f32_e32 v1, v3, v1
	v_lshlrev_b32_e32 v2, 16, v113
	v_and_b32_e32 v3, 0xffff0000, v113
	v_mul_f32_e32 v2, v4, v2
	v_mul_f32_e32 v3, v5, v3
	v_cvt_pk_bf16_f32 v0, v0, v1
	v_cvt_pk_bf16_f32 v1, v2, v3
	v_lshlrev_b32_e32 v2, 16, v6
	v_and_b32_e32 v3, 0xffff0000, v6
	v_mul_f32_e32 v4, v12, v34
	v_mul_f32_e32 v5, v13, v34
	s_mov_b64 s[2:3], 0x200
	v_mul_f32_e32 v2, v4, v2
	v_mul_f32_e32 v3, v5, v3
	v_lshlrev_b32_e32 v4, 16, v7
	v_and_b32_e32 v5, 0xffff0000, v7
	v_mul_f32_e32 v6, v14, v34
	v_mul_f32_e32 v7, v15, v34
	v_cvt_pk_bf16_f32 v2, v2, v3
	v_mul_f32_e32 v4, v6, v4
	v_mul_f32_e32 v5, v7, v5
	v_lshl_add_u64 v[32:33], v[36:37], 0, s[2:3]
	v_cvt_pk_bf16_f32 v3, v4, v5
	v_permlane32_swap_b32_e32 v0, v2
	s_nop 0
	v_permlane32_swap_b32_e32 v1, v3
	s_branch .LBB0_876
